# P2 q/k-norm epilogue phase 1: the 32 serialized ds_bpermute round trips per tile (shfl_xor 16/32 of the row sums of squares) replaced by v_permlane16_swap / v_permlane32_swap
# baseline (speedup 1.0000x reference)
.LBB0_338:
	s_andn2_b64 vcc, exec, s[8:9]
	s_cbranch_vccnz .LBB0_153
	s_cmp_gt_i32 s12, 7
	s_cselect_b64 s[78:79], -1, 0
	s_cmp_lt_i32 s12, 8
	s_cselect_b32 s2, s17, s19
	s_cselect_b32 s8, s16, s18
	s_lshl_b32 s76, s89, 2
	s_add_u32 s8, s8, s76
	s_addc_u32 s9, s2, 0
	v_lshlrev_b32_e32 v172, 2, v160
	global_load_dwordx4 v[132:135], v172, s[8:9]
	global_load_dwordx4 v[128:131], v172, s[8:9] offset:128
	v_mul_f32_e32 v138, v125, v125
	v_mul_f32_e32 v139, v127, v127
	v_fmac_f32_e32 v138, v124, v124
	v_fmac_f32_e32 v139, v126, v126
	v_and_b32_e32 v137, 64, v210
	v_add_f32_e32 v138, v138, v139
	v_mul_f32_e32 v139, v121, v121
	v_xor_b32_e32 v136, 16, v210
	v_add_u32_e32 v137, 64, v137
	v_fmac_f32_e32 v139, v120, v120
	v_cmp_lt_i32_e32 vcc, v136, v137
	v_add_f32_e32 v138, v138, v139
	v_mul_f32_e32 v139, v123, v123
	v_cndmask_b32_e32 v136, v210, v136, vcc
	v_fmac_f32_e32 v139, v122, v122
	v_lshlrev_b32_e32 v136, 2, v136
	v_add_f32_e32 v138, v139, v138
	v_mov_b32_e32 v139, v138
	v_mov_b32_e32 v214, v138
	s_nop 1
	v_permlane16_swap_b32_e32 v139, v214
	v_xor_b32_e32 v140, 32, v210
	v_cmp_lt_i32_e32 vcc, v140, v137
	s_waitcnt lgkmcnt(0)
	v_add_f32_e32 v138, v139, v214
	v_cndmask_b32_e32 v137, v210, v140, vcc
	v_lshlrev_b32_e32 v137, 2, v137
	v_mov_b32_e32 v139, v138
	v_mov_b32_e32 v214, v138
	s_nop 1
	v_permlane32_swap_b32_e32 v214, v139
	s_and_saveexec_b64 s[8:9], s[4:5]
	s_cbranch_execz .LBB0_341
	s_waitcnt lgkmcnt(0)
	v_add_f32_e32 v138, v138, v139
	ds_write_b32 v200, v138
.LBB0_341:
	s_or_b64 exec, exec, s[8:9]
	v_mul_f32_e32 v138, v117, v117
	s_waitcnt lgkmcnt(0)
	v_mul_f32_e32 v139, v119, v119
	v_fmac_f32_e32 v138, v116, v116
	v_fmac_f32_e32 v139, v118, v118
	v_add_f32_e32 v138, v138, v139
	v_mul_f32_e32 v139, v113, v113
	v_fmac_f32_e32 v139, v112, v112
	v_add_f32_e32 v138, v138, v139
	v_mul_f32_e32 v139, v115, v115
	v_fmac_f32_e32 v139, v114, v114
	v_add_f32_e32 v138, v139, v138
	v_mov_b32_e32 v139, v138
	v_mov_b32_e32 v214, v138
	s_nop 1
	v_permlane16_swap_b32_e32 v139, v214
	s_waitcnt lgkmcnt(0)
	v_add_f32_e32 v138, v139, v214
	v_mov_b32_e32 v139, v138
	v_mov_b32_e32 v214, v138
	s_nop 1
	v_permlane32_swap_b32_e32 v214, v139
	s_and_saveexec_b64 s[8:9], s[4:5]
	s_cbranch_execz .LBB0_343
	s_waitcnt lgkmcnt(0)
	v_add_f32_e32 v138, v138, v139
	ds_write_b32 v200, v138 offset:16
.LBB0_343:
	s_or_b64 exec, exec, s[8:9]
	v_mul_f32_e32 v138, v109, v109
	s_waitcnt lgkmcnt(0)
	v_mul_f32_e32 v139, v111, v111
	v_fmac_f32_e32 v138, v108, v108
	v_fmac_f32_e32 v139, v110, v110
	v_add_f32_e32 v138, v138, v139
	v_mul_f32_e32 v139, v105, v105
	v_fmac_f32_e32 v139, v104, v104
	v_add_f32_e32 v138, v138, v139
	v_mul_f32_e32 v139, v107, v107
	v_fmac_f32_e32 v139, v106, v106
	v_add_f32_e32 v138, v139, v138
	v_mov_b32_e32 v139, v138
	v_mov_b32_e32 v214, v138
	s_nop 1
	v_permlane16_swap_b32_e32 v139, v214
	s_waitcnt lgkmcnt(0)
	v_add_f32_e32 v138, v139, v214
	v_mov_b32_e32 v139, v138
	v_mov_b32_e32 v214, v138
	s_nop 1
	v_permlane32_swap_b32_e32 v214, v139
	s_and_saveexec_b64 s[8:9], s[4:5]
	s_cbranch_execz .LBB0_345
	s_waitcnt lgkmcnt(0)
	v_add_f32_e32 v138, v138, v139
	ds_write_b32 v201, v138
.LBB0_345:
	s_or_b64 exec, exec, s[8:9]
	v_mul_f32_e32 v138, v101, v101
	s_waitcnt lgkmcnt(0)
	v_mul_f32_e32 v139, v103, v103
	v_fmac_f32_e32 v138, v100, v100
	v_fmac_f32_e32 v139, v102, v102
	v_add_f32_e32 v138, v138, v139
	v_mul_f32_e32 v139, v97, v97
	v_fmac_f32_e32 v139, v96, v96
	v_add_f32_e32 v138, v138, v139
	v_mul_f32_e32 v139, v99, v99
	v_fmac_f32_e32 v139, v98, v98
	v_add_f32_e32 v138, v139, v138
	v_mov_b32_e32 v139, v138
	v_mov_b32_e32 v214, v138
	s_nop 1
	v_permlane16_swap_b32_e32 v139, v214
	s_waitcnt lgkmcnt(0)
	v_add_f32_e32 v138, v139, v214
	v_mov_b32_e32 v139, v138
	v_mov_b32_e32 v214, v138
	s_nop 1
	v_permlane32_swap_b32_e32 v214, v139
	s_and_saveexec_b64 s[8:9], s[4:5]
	s_cbranch_execz .LBB0_347
	s_waitcnt lgkmcnt(0)
	v_add_f32_e32 v138, v138, v139
	ds_write_b32 v201, v138 offset:16
.LBB0_347:
	s_or_b64 exec, exec, s[8:9]
	v_mul_f32_e32 v138, v93, v93
	s_waitcnt lgkmcnt(0)
	v_mul_f32_e32 v139, v95, v95
	v_fmac_f32_e32 v138, v92, v92
	v_fmac_f32_e32 v139, v94, v94
	v_add_f32_e32 v138, v138, v139
	v_mul_f32_e32 v139, v89, v89
	v_fmac_f32_e32 v139, v88, v88
	v_add_f32_e32 v138, v138, v139
	v_mul_f32_e32 v139, v91, v91
	v_fmac_f32_e32 v139, v90, v90
	v_add_f32_e32 v138, v139, v138
	v_mov_b32_e32 v139, v138
	v_mov_b32_e32 v214, v138
	s_nop 1
	v_permlane16_swap_b32_e32 v139, v214
	s_waitcnt lgkmcnt(0)
	v_add_f32_e32 v138, v139, v214
	v_mov_b32_e32 v139, v138
	v_mov_b32_e32 v214, v138
	s_nop 1
	v_permlane32_swap_b32_e32 v214, v139
	s_and_saveexec_b64 s[8:9], s[4:5]
	s_cbranch_execz .LBB0_349
	s_waitcnt lgkmcnt(0)
	v_add_f32_e32 v138, v138, v139
	ds_write_b32 v202, v138
.LBB0_349:
	s_or_b64 exec, exec, s[8:9]
	v_mul_f32_e32 v138, v85, v85
	s_waitcnt lgkmcnt(0)
	v_mul_f32_e32 v139, v87, v87
	v_fmac_f32_e32 v138, v84, v84
	v_fmac_f32_e32 v139, v86, v86
	v_add_f32_e32 v138, v138, v139
	v_mul_f32_e32 v139, v81, v81
	v_fmac_f32_e32 v139, v80, v80
	v_add_f32_e32 v138, v138, v139
	v_mul_f32_e32 v139, v83, v83
	v_fmac_f32_e32 v139, v82, v82
	v_add_f32_e32 v138, v139, v138
	v_mov_b32_e32 v139, v138
	v_mov_b32_e32 v214, v138
	s_nop 1
	v_permlane16_swap_b32_e32 v139, v214
	s_waitcnt lgkmcnt(0)
	v_add_f32_e32 v138, v139, v214
	v_mov_b32_e32 v139, v138
	v_mov_b32_e32 v214, v138
	s_nop 1
	v_permlane32_swap_b32_e32 v214, v139
	s_and_saveexec_b64 s[8:9], s[4:5]
	s_cbranch_execz .LBB0_351
	s_waitcnt lgkmcnt(0)
	v_add_f32_e32 v138, v138, v139
	ds_write_b32 v202, v138 offset:16
.LBB0_351:
	s_or_b64 exec, exec, s[8:9]
	v_mul_f32_e32 v138, v77, v77
	s_waitcnt lgkmcnt(0)
	v_mul_f32_e32 v139, v79, v79
	v_fmac_f32_e32 v138, v76, v76
	v_fmac_f32_e32 v139, v78, v78
	v_add_f32_e32 v138, v138, v139
	v_mul_f32_e32 v139, v73, v73
	v_fmac_f32_e32 v139, v72, v72
	v_add_f32_e32 v138, v138, v139
	v_mul_f32_e32 v139, v75, v75
	v_fmac_f32_e32 v139, v74, v74
	v_add_f32_e32 v138, v139, v138
	v_mov_b32_e32 v139, v138
	v_mov_b32_e32 v214, v138
	s_nop 1
	v_permlane16_swap_b32_e32 v139, v214
	s_waitcnt lgkmcnt(0)
	v_add_f32_e32 v138, v139, v214
	v_mov_b32_e32 v139, v138
	v_mov_b32_e32 v214, v138
	s_nop 1
	v_permlane32_swap_b32_e32 v214, v139
	s_and_saveexec_b64 s[8:9], s[4:5]
	s_cbranch_execz .LBB0_353
	s_waitcnt lgkmcnt(0)
	v_add_f32_e32 v138, v138, v139
	ds_write_b32 v203, v138
.LBB0_353:
	s_or_b64 exec, exec, s[8:9]
	v_mul_f32_e32 v138, v69, v69
	s_waitcnt lgkmcnt(0)
	v_mul_f32_e32 v139, v71, v71
	v_fmac_f32_e32 v138, v68, v68
	v_fmac_f32_e32 v139, v70, v70
	v_add_f32_e32 v138, v138, v139
	v_mul_f32_e32 v139, v65, v65
	v_fmac_f32_e32 v139, v64, v64
	v_add_f32_e32 v138, v138, v139
	v_mul_f32_e32 v139, v67, v67
	v_fmac_f32_e32 v139, v66, v66
	v_add_f32_e32 v138, v139, v138
	v_mov_b32_e32 v139, v138
	v_mov_b32_e32 v214, v138
	s_nop 1
	v_permlane16_swap_b32_e32 v139, v214
	s_waitcnt lgkmcnt(0)
	v_add_f32_e32 v138, v139, v214
	v_mov_b32_e32 v139, v138
	v_mov_b32_e32 v214, v138
	s_nop 1
	v_permlane32_swap_b32_e32 v214, v139
	s_and_saveexec_b64 s[8:9], s[4:5]
	s_cbranch_execz .LBB0_355
	s_waitcnt lgkmcnt(0)
	v_add_f32_e32 v138, v138, v139
	ds_write_b32 v203, v138 offset:16
.LBB0_355:
	s_or_b64 exec, exec, s[8:9]
	v_mul_f32_e32 v138, v61, v61
	s_waitcnt lgkmcnt(0)
	v_mul_f32_e32 v139, v63, v63
	v_fmac_f32_e32 v138, v60, v60
	v_fmac_f32_e32 v139, v62, v62
	v_add_f32_e32 v138, v138, v139
	v_mul_f32_e32 v139, v57, v57
	v_fmac_f32_e32 v139, v56, v56
	v_add_f32_e32 v138, v138, v139
	v_mul_f32_e32 v139, v59, v59
	v_fmac_f32_e32 v139, v58, v58
	v_add_f32_e32 v138, v139, v138
	v_mov_b32_e32 v139, v138
	v_mov_b32_e32 v214, v138
	s_nop 1
	v_permlane16_swap_b32_e32 v139, v214
	s_waitcnt lgkmcnt(0)
	v_add_f32_e32 v138, v139, v214
	v_mov_b32_e32 v139, v138
	v_mov_b32_e32 v214, v138
	s_nop 1
	v_permlane32_swap_b32_e32 v214, v139
	s_and_saveexec_b64 s[8:9], s[4:5]
	s_cbranch_execz .LBB0_357
	s_waitcnt lgkmcnt(0)
	v_add_f32_e32 v138, v138, v139
	ds_write_b32 v204, v138
.LBB0_357:
	s_or_b64 exec, exec, s[8:9]
	v_mul_f32_e32 v138, v53, v53
	s_waitcnt lgkmcnt(0)
	v_mul_f32_e32 v139, v55, v55
	v_fmac_f32_e32 v138, v52, v52
	v_fmac_f32_e32 v139, v54, v54
	v_add_f32_e32 v138, v138, v139
	v_mul_f32_e32 v139, v49, v49
	v_fmac_f32_e32 v139, v48, v48
	v_add_f32_e32 v138, v138, v139
	v_mul_f32_e32 v139, v51, v51
	v_fmac_f32_e32 v139, v50, v50
	v_add_f32_e32 v138, v139, v138
	v_mov_b32_e32 v139, v138
	v_mov_b32_e32 v214, v138
	s_nop 1
	v_permlane16_swap_b32_e32 v139, v214
	s_waitcnt lgkmcnt(0)
	v_add_f32_e32 v138, v139, v214
	v_mov_b32_e32 v139, v138
	v_mov_b32_e32 v214, v138
	s_nop 1
	v_permlane32_swap_b32_e32 v214, v139
	s_and_saveexec_b64 s[8:9], s[4:5]
	s_cbranch_execz .LBB0_359
	s_waitcnt lgkmcnt(0)
	v_add_f32_e32 v138, v138, v139
	ds_write_b32 v204, v138 offset:16
.LBB0_359:
	s_or_b64 exec, exec, s[8:9]
	v_mul_f32_e32 v138, v45, v45
	s_waitcnt lgkmcnt(0)
	v_mul_f32_e32 v139, v47, v47
	v_fmac_f32_e32 v138, v44, v44
	v_fmac_f32_e32 v139, v46, v46
	v_add_f32_e32 v138, v138, v139
	v_mul_f32_e32 v139, v41, v41
	v_fmac_f32_e32 v139, v40, v40
	v_add_f32_e32 v138, v138, v139
	v_mul_f32_e32 v139, v43, v43
	v_fmac_f32_e32 v139, v42, v42
	v_add_f32_e32 v138, v139, v138
	v_mov_b32_e32 v139, v138
	v_mov_b32_e32 v214, v138
	s_nop 1
	v_permlane16_swap_b32_e32 v139, v214
	s_waitcnt lgkmcnt(0)
	v_add_f32_e32 v138, v139, v214
	v_mov_b32_e32 v139, v138
	v_mov_b32_e32 v214, v138
	s_nop 1
	v_permlane32_swap_b32_e32 v214, v139
	s_and_saveexec_b64 s[8:9], s[4:5]
	s_cbranch_execz .LBB0_361
	s_waitcnt lgkmcnt(0)
	v_add_f32_e32 v138, v138, v139
	ds_write_b32 v205, v138
.LBB0_361:
	s_or_b64 exec, exec, s[8:9]
	v_mul_f32_e32 v138, v37, v37
	s_waitcnt lgkmcnt(0)
	v_mul_f32_e32 v139, v39, v39
	v_fmac_f32_e32 v138, v36, v36
	v_fmac_f32_e32 v139, v38, v38
	v_add_f32_e32 v138, v138, v139
	v_mul_f32_e32 v139, v33, v33
	v_fmac_f32_e32 v139, v32, v32
	v_add_f32_e32 v138, v138, v139
	v_mul_f32_e32 v139, v35, v35
	v_fmac_f32_e32 v139, v34, v34
	v_add_f32_e32 v138, v139, v138
	v_mov_b32_e32 v139, v138
	v_mov_b32_e32 v214, v138
	s_nop 1
	v_permlane16_swap_b32_e32 v139, v214
	s_waitcnt lgkmcnt(0)
	v_add_f32_e32 v138, v139, v214
	v_mov_b32_e32 v139, v138
	v_mov_b32_e32 v214, v138
	s_nop 1
	v_permlane32_swap_b32_e32 v214, v139
	s_and_saveexec_b64 s[8:9], s[4:5]
	s_cbranch_execz .LBB0_363
	s_waitcnt lgkmcnt(0)
	v_add_f32_e32 v138, v138, v139
	ds_write_b32 v205, v138 offset:16
.LBB0_363:
	s_or_b64 exec, exec, s[8:9]
	v_mul_f32_e32 v138, v29, v29
	s_waitcnt lgkmcnt(0)
	v_mul_f32_e32 v139, v31, v31
	v_fmac_f32_e32 v138, v28, v28
	v_fmac_f32_e32 v139, v30, v30
	v_add_f32_e32 v138, v138, v139
	v_mul_f32_e32 v139, v25, v25
	v_fmac_f32_e32 v139, v24, v24
	v_add_f32_e32 v138, v138, v139
	v_mul_f32_e32 v139, v27, v27
	v_fmac_f32_e32 v139, v26, v26
	v_add_f32_e32 v138, v139, v138
	v_mov_b32_e32 v139, v138
	v_mov_b32_e32 v214, v138
	s_nop 1
	v_permlane16_swap_b32_e32 v139, v214
	s_waitcnt lgkmcnt(0)
	v_add_f32_e32 v138, v139, v214
	v_mov_b32_e32 v139, v138
	v_mov_b32_e32 v214, v138
	s_nop 1
	v_permlane32_swap_b32_e32 v214, v139
	s_and_saveexec_b64 s[8:9], s[4:5]
	s_cbranch_execz .LBB0_365
	s_waitcnt lgkmcnt(0)
	v_add_f32_e32 v138, v138, v139
	ds_write_b32 v206, v138
.LBB0_365:
	s_or_b64 exec, exec, s[8:9]
	v_mul_f32_e32 v138, v21, v21
	s_waitcnt lgkmcnt(0)
	v_mul_f32_e32 v139, v23, v23
	v_fmac_f32_e32 v138, v20, v20
	v_fmac_f32_e32 v139, v22, v22
	v_add_f32_e32 v138, v138, v139
	v_mul_f32_e32 v139, v17, v17
	v_fmac_f32_e32 v139, v16, v16
	v_add_f32_e32 v138, v138, v139
	v_mul_f32_e32 v139, v19, v19
	v_fmac_f32_e32 v139, v18, v18
	v_add_f32_e32 v138, v139, v138
	v_mov_b32_e32 v139, v138
	v_mov_b32_e32 v214, v138
	s_nop 1
	v_permlane16_swap_b32_e32 v139, v214
	s_waitcnt lgkmcnt(0)
	v_add_f32_e32 v138, v139, v214
	v_mov_b32_e32 v139, v138
	v_mov_b32_e32 v214, v138
	s_nop 1
	v_permlane32_swap_b32_e32 v214, v139
	s_and_saveexec_b64 s[8:9], s[4:5]
	s_cbranch_execz .LBB0_367
	s_waitcnt lgkmcnt(0)
	v_add_f32_e32 v138, v138, v139
	ds_write_b32 v206, v138 offset:16
.LBB0_367:
	s_or_b64 exec, exec, s[8:9]
	v_mul_f32_e32 v138, v13, v13
	s_waitcnt lgkmcnt(0)
	v_mul_f32_e32 v139, v15, v15
	v_fmac_f32_e32 v138, v12, v12
	v_fmac_f32_e32 v139, v14, v14
	v_add_f32_e32 v138, v138, v139
	v_mul_f32_e32 v139, v9, v9
	v_fmac_f32_e32 v139, v8, v8
	v_add_f32_e32 v138, v138, v139
	v_mul_f32_e32 v139, v11, v11
	v_fmac_f32_e32 v139, v10, v10
	v_add_f32_e32 v138, v139, v138
	v_mov_b32_e32 v139, v138
	v_mov_b32_e32 v214, v138
	s_nop 1
	v_permlane16_swap_b32_e32 v139, v214
	s_waitcnt lgkmcnt(0)
	v_add_f32_e32 v138, v139, v214
	v_mov_b32_e32 v139, v138
	v_mov_b32_e32 v214, v138
	s_nop 1
	v_permlane32_swap_b32_e32 v214, v139
	s_and_saveexec_b64 s[8:9], s[4:5]
	s_cbranch_execz .LBB0_369
	s_waitcnt lgkmcnt(0)
	v_add_f32_e32 v138, v138, v139
	ds_write_b32 v207, v138
.LBB0_369:
	s_or_b64 exec, exec, s[8:9]
	v_mul_f32_e32 v138, v5, v5
	s_waitcnt lgkmcnt(0)
	v_mul_f32_e32 v139, v7, v7
	v_fmac_f32_e32 v138, v4, v4
	v_fmac_f32_e32 v139, v6, v6
	v_add_f32_e32 v138, v138, v139
	v_mul_f32_e32 v139, v1, v1
	v_fmac_f32_e32 v139, v0, v0
	v_add_f32_e32 v138, v138, v139
	v_mul_f32_e32 v139, v3, v3
	v_fmac_f32_e32 v139, v2, v2
	v_add_f32_e32 v138, v139, v138
	v_mov_b32_e32 v136, v138
	v_mov_b32_e32 v214, v138
	s_nop 1
	v_permlane16_swap_b32_e32 v136, v214
	s_waitcnt lgkmcnt(0)
	v_add_f32_e32 v136, v136, v214
	v_mov_b32_e32 v137, v136
	v_mov_b32_e32 v214, v136
	s_nop 1
	v_permlane32_swap_b32_e32 v214, v137
	s_and_saveexec_b64 s[8:9], s[4:5]
	s_cbranch_execz .LBB0_371
	s_waitcnt lgkmcnt(0)
	v_add_f32_e32 v136, v136, v137
	ds_write_b32 v207, v136 offset:16
